# combined: QKU rstd fill reuse + K-loops without s_setprio toggles + shorter seam spin sleeps
# speedup vs baseline: 1.0153x; 1.0153x over previous
; __device__ __forceinline__ unsigned xb_ld(unsigned* p)              { return __hip_atomic_load(p, __ATOMIC_RELAXED, __HIP_MEMORY_SCOPE_AGENT); }
; __device__ __forceinline__ unsigned xb_add(unsigned* p, unsigned v) { return __hip_atomic_fetch_add(p, v, __ATOMIC_RELAXED, __HIP_MEMORY_SCOPE_AGENT); }
; #define XB_SPIN(cond, bar) do { unsigned _sp = 0; while (cond) { __builtin_amdgcn_s_sleep(8); \
;     if ((++_sp & 255u) == 0u) { if (xb_ld(&(bar)[XB_TMO])) break; if (_sp > XB_SPIN_CAP) { atomicAdd(&(bar)[XB_TMO], 1u); break; } } } } while (0)
; __device__ __forceinline__ void xcd_barrier(const XcdBarrier& b) {
;     ...
;             else XB_SPIN(xb_ld(&bar[XB_TOPGEN]) == tg, bar);
;             __builtin_amdgcn_fence(__ATOMIC_ACQUIRE, "agent");
;             xb_add(&bar[XB_XGEN(b.x)], 1u);
;             asm volatile("s_waitcnt vmcnt(0)" ::: "memory");
;         } else {
;             XB_SPIN(xb_ld(&bar[XB_XGEN(b.x)]) == gen, bar);
.LBB0_410:
	s_and_b32 s6, s5, 0xff
	s_mov_b64 s[48:49], -1
	s_cmp_lg_u32 s6, 0
	s_mov_b64 s[52:53], -1
	s_sleep 2
	s_cbranch_scc1 .LBB0_413
	v_readlane_b32 s6, v252, 34
	v_readlane_b32 s7, v252, 35
	s_nop 4
	global_load_dword v2, v1, s[6:7] sc1
	s_waitcnt vmcnt(0)
	v_cmp_eq_u32_e32 vcc, 0, v2
	s_cbranch_vccnz .LBB0_415
	s_mov_b64 s[52:53], 0
	s_mov_b64 s[50:51], -1

; __device__ __forceinline__ unsigned xb_ld(unsigned* p)              { return __hip_atomic_load(p, __ATOMIC_RELAXED, __HIP_MEMORY_SCOPE_AGENT); }
; __device__ __forceinline__ unsigned xb_add(unsigned* p, unsigned v) { return __hip_atomic_fetch_add(p, v, __ATOMIC_RELAXED, __HIP_MEMORY_SCOPE_AGENT); }
; #define XB_SPIN(cond, bar) do { unsigned _sp = 0; while (cond) { __builtin_amdgcn_s_sleep(8); \
;     if ((++_sp & 255u) == 0u) { if (xb_ld(&(bar)[XB_TMO])) break; if (_sp > XB_SPIN_CAP) { atomicAdd(&(bar)[XB_TMO], 1u); break; } } } } while (0)
; __device__ __forceinline__ void xcd_barrier(const XcdBarrier& b) {
;     ...
;             else XB_SPIN(xb_ld(&bar[XB_TOPGEN]) == tg, bar);
;             __builtin_amdgcn_fence(__ATOMIC_ACQUIRE, "agent");
;             xb_add(&bar[XB_XGEN(b.x)], 1u);
;             asm volatile("s_waitcnt vmcnt(0)" ::: "memory");
;         } else {
;             XB_SPIN(xb_ld(&bar[XB_XGEN(b.x)]) == gen, bar);
.LBB0_508:
	s_and_b32 s5, s4, 0xff
	s_mov_b64 s[50:51], -1
	s_cmp_lg_u32 s5, 0
	s_mov_b64 s[54:55], -1
	s_sleep 2
	s_cbranch_scc1 .LBB0_511
	v_readlane_b32 s12, v252, 34
	v_readlane_b32 s13, v252, 35
	s_nop 4
	global_load_dword v2, v1, s[12:13] sc1
	s_waitcnt vmcnt(0)
	v_cmp_eq_u32_e32 vcc, 0, v2
	s_cbranch_vccnz .LBB0_513
	s_mov_b64 s[54:55], 0
	s_mov_b64 s[52:53], -1

; __device__ __forceinline__ unsigned xb_ld(unsigned* p)              { return __hip_atomic_load(p, __ATOMIC_RELAXED, __HIP_MEMORY_SCOPE_AGENT); }
; __device__ __forceinline__ unsigned xb_add(unsigned* p, unsigned v) { return __hip_atomic_fetch_add(p, v, __ATOMIC_RELAXED, __HIP_MEMORY_SCOPE_AGENT); }
; #define XB_SPIN(cond, bar) do { unsigned _sp = 0; while (cond) { __builtin_amdgcn_s_sleep(8); \
;     if ((++_sp & 255u) == 0u) { if (xb_ld(&(bar)[XB_TMO])) break; if (_sp > XB_SPIN_CAP) { atomicAdd(&(bar)[XB_TMO], 1u); break; } } } } while (0)
; __device__ __forceinline__ void xcd_barrier(const XcdBarrier& b) {
;     ...
;             else XB_SPIN(xb_ld(&bar[XB_TOPGEN]) == tg, bar);
;             __builtin_amdgcn_fence(__ATOMIC_ACQUIRE, "agent");
;             xb_add(&bar[XB_XGEN(b.x)], 1u);
;             asm volatile("s_waitcnt vmcnt(0)" ::: "memory");
;         } else {
;             XB_SPIN(xb_ld(&bar[XB_XGEN(b.x)]) == gen, bar);
.LBB0_1046:
	s_and_b32 s5, s4, 0xff
	s_mov_b64 s[48:49], -1
	s_cmp_lg_u32 s5, 0
	s_mov_b64 s[52:53], -1
	s_sleep 2
	s_cbranch_scc1 .LBB0_1049
	v_readlane_b32 s6, v252, 34
	v_readlane_b32 s7, v252, 35
	s_nop 4
	global_load_dword v2, v1, s[6:7] sc1
	s_waitcnt vmcnt(0)
	v_cmp_eq_u32_e32 vcc, 0, v2
	s_cbranch_vccnz .LBB0_1051
	s_mov_b64 s[52:53], 0
	s_mov_b64 s[50:51], -1

; __device__ __forceinline__ unsigned xb_ld(unsigned* p)              { return __hip_atomic_load(p, __ATOMIC_RELAXED, __HIP_MEMORY_SCOPE_AGENT); }
; __device__ __forceinline__ unsigned xb_add(unsigned* p, unsigned v) { return __hip_atomic_fetch_add(p, v, __ATOMIC_RELAXED, __HIP_MEMORY_SCOPE_AGENT); }
; #define XB_SPIN(cond, bar) do { unsigned _sp = 0; while (cond) { __builtin_amdgcn_s_sleep(8); \
;     if ((++_sp & 255u) == 0u) { if (xb_ld(&(bar)[XB_TMO])) break; if (_sp > XB_SPIN_CAP) { atomicAdd(&(bar)[XB_TMO], 1u); break; } } } } while (0)
; __device__ __forceinline__ void xcd_barrier(const XcdBarrier& b) {
;     ...
;             else XB_SPIN(xb_ld(&bar[XB_TOPGEN]) == tg, bar);
;             __builtin_amdgcn_fence(__ATOMIC_ACQUIRE, "agent");
;             xb_add(&bar[XB_XGEN(b.x)], 1u);
;             asm volatile("s_waitcnt vmcnt(0)" ::: "memory");
;         } else {
;             XB_SPIN(xb_ld(&bar[XB_XGEN(b.x)]) == gen, bar);
.LBB0_1154:
	s_and_b32 s5, s4, 0xff
	s_mov_b64 s[50:51], -1
	s_cmp_lg_u32 s5, 0
	s_mov_b64 s[54:55], -1
	s_sleep 2
	s_cbranch_scc1 .LBB0_1157
	v_readlane_b32 s6, v252, 34
	v_readlane_b32 s7, v252, 35
	s_nop 4
	global_load_dword v2, v1, s[6:7] sc1
	s_waitcnt vmcnt(0)
	v_cmp_eq_u32_e32 vcc, 0, v2
	s_cbranch_vccnz .LBB0_1159
	s_mov_b64 s[54:55], 0
	s_mov_b64 s[52:53], -1
